# select pass 1: 16-bin per-lane scan as 4 conflict-free ds_read_b128
# baseline (speedup 1.0000x reference)
; template <int PASS>
; DI void sel_pass(SelSmem* S, const uint32_t (&sk)[32][2], int ntiles, uint32_t (&pf)[2]) {
;     ...
;   {
;     constexpr int PER = (PASS == 0 || PASS == 3) ? 64 : 16;
;     const int pair = wave >> 1, sh = (wave & 1) * 16;
;     const uint32_t need = S->need[wave];
;     const uint32_t prevp = S->pfx[wave];
;     const uint32_t* hp = &S->hist[pair][lane * PER];
;     uint32_t tot = 0;
;     for (int c = 0; c < PER; ++c) tot += (hp[(c + lane) & (PER - 1)] >> sh) & 0xffffu;
;     uint32_t incl = tot;
; #pragma unroll
;     for (int off = 1; off < 64; off <<= 1) {
;       uint32_t v = __shfl_down(incl, off);
;       if (lane + off < 64) incl += v;
;     }
;     const uint32_t sfx = incl - tot;
;     const bool cross = (sfx < need) && (need <= sfx + tot);
;     const unsigned long long cm = __ballot(cross);
;     if (cm != 0ull) {
;       const int L = __builtin_ctzll(cm);
;       const uint32_t cumbase = (uint32_t)__shfl((int)sfx, L);
;       const uint32_t cnt = (lane < PER) ? ((S->hist[pair][L * PER + lane] >> sh) & 0xffffu) : 0u;
.LBB0_783:
	s_lshl_b32 s0, s15, 7
	v_and_b32_e32 v0, 63, v5
	s_and_b32 s15, s0, 0xffffc000
	v_add_u32_e32 v15, 1, v5
	v_lshl_or_b32 v13, v0, 6, s15
	v_and_b32_e32 v14, 15, v5
	v_and_b32_e32 v15, 15, v15
	v_lshl_or_b32 v14, v14, 2, v13
	v_lshl_or_b32 v15, v15, 2, v13
	s_waitcnt lgkmcnt(0)
	s_barrier
	s_lshl_b32 s52, s44, 4
	s_lshl_b32 s16, s44, 2
	v_mov_b32_e32 v1, s16
	ds_read_b32 v1, v1 offset:32784
	v_bfe_u32 v14, v0, 2, 2
	v_lshl_or_b32 v15, v14, 4, v13
	ds_read_b128 v[96:99], v15
	v_add_u32_e32 v15, 1, v14
	v_and_b32_e32 v15, 3, v15
	v_lshl_or_b32 v15, v15, 4, v13
	ds_read_b128 v[100:103], v15
	v_add_u32_e32 v15, 2, v14
	v_and_b32_e32 v15, 3, v15
	v_lshl_or_b32 v15, v15, 4, v13
	ds_read_b128 v[104:107], v15
	v_add_u32_e32 v15, 3, v14
	v_and_b32_e32 v15, 3, v15
	v_lshl_or_b32 v15, v15, 4, v13
	ds_read_b128 v[130:133], v15
	v_cmp_eq_u32_e64 s[44:45], 63, v0
	v_cmp_gt_u32_e64 s[46:47], 62, v0
	v_cmp_gt_u32_e64 s[48:49], 60, v0
	v_cmp_gt_u32_e64 s[0:1], 56, v0
	v_cmp_gt_u32_e32 vcc, 48, v0
	v_mov_b32_e32 v16, 0
	s_waitcnt lgkmcnt(0)
	v_bfe_u32 v96, v96, s52, 16
	v_bfe_u32 v97, v97, s52, 16
	v_bfe_u32 v98, v98, s52, 16
	v_bfe_u32 v99, v99, s52, 16
	v_add3_u32 v16, v16, v96, v97
	v_add3_u32 v16, v16, v98, v99
	v_bfe_u32 v100, v100, s52, 16
	v_bfe_u32 v101, v101, s52, 16
	v_bfe_u32 v102, v102, s52, 16
	v_bfe_u32 v103, v103, s52, 16
	v_add3_u32 v16, v16, v100, v101
	v_add3_u32 v16, v16, v102, v103
	v_bfe_u32 v104, v104, s52, 16
	v_bfe_u32 v105, v105, s52, 16
	v_bfe_u32 v106, v106, s52, 16
	v_bfe_u32 v107, v107, s52, 16
	v_add3_u32 v16, v16, v104, v105
	v_add3_u32 v16, v16, v106, v107
	v_bfe_u32 v130, v130, s52, 16
	v_bfe_u32 v131, v131, s52, 16
	v_bfe_u32 v132, v132, s52, 16
	v_bfe_u32 v133, v133, s52, 16
	v_add3_u32 v16, v16, v130, v131
	v_add3_u32 v16, v16, v132, v133
	v_mov_b32_e32 v5, v16
	ds_bpermute_b32 v13, v7, v5
	s_waitcnt lgkmcnt(0)
	v_cndmask_b32_e64 v13, v13, 0, s[44:45]
	v_add_u32_e32 v13, v5, v13
	ds_bpermute_b32 v14, v8, v13
	s_waitcnt lgkmcnt(0)
	v_cndmask_b32_e64 v14, 0, v14, s[46:47]
	v_add_u32_e32 v13, v13, v14
	ds_bpermute_b32 v14, v9, v13
	s_waitcnt lgkmcnt(0)
	v_cndmask_b32_e64 v14, 0, v14, s[48:49]
	v_add_u32_e32 v13, v13, v14
	ds_bpermute_b32 v14, v10, v13
	s_waitcnt lgkmcnt(0)
	v_cndmask_b32_e64 v14, 0, v14, s[0:1]
	v_add_u32_e32 v13, v13, v14
	ds_bpermute_b32 v14, v11, v13
	s_waitcnt lgkmcnt(0)
	v_cndmask_b32_e32 v14, 0, v14, vcc
	v_add_u32_e32 v13, v13, v14
	ds_bpermute_b32 v14, v12, v13
	v_cmp_gt_u32_e32 vcc, 32, v0
	s_waitcnt lgkmcnt(0)
	s_nop 0
	v_cndmask_b32_e32 v14, 0, v14, vcc
	v_add_u32_e32 v14, v13, v14
	v_sub_u32_e32 v13, v14, v5
	v_cmp_lt_u32_e32 vcc, v13, v1
	v_cmp_le_u32_e64 s[50:51], v1, v14
	s_and_b64 vcc, s[50:51], vcc
	v_cndmask_b32_e64 v5, 0, 1, vcc
	v_cmp_ne_u32_e64 s[50:51], 0, v5
	s_cbranch_vccz .LBB0_792
	s_ff1_i32_b64 s53, s[50:51]
	v_and_or_b32 v14, v213, 64, s53
	v_mov_b32_e32 v5, s16
	v_lshlrev_b32_e32 v14, 2, v14
	ds_read_b32 v5, v5 offset:32768
	ds_bpermute_b32 v14, v14, v13
	v_cmp_lt_u32_e32 vcc, 15, v0
	v_cmp_gt_u32_e64 s[50:51], 16, v0
	v_mov_b32_e32 v13, 0
	s_and_saveexec_b64 s[18:19], s[50:51]
	s_cbranch_execz .LBB0_786
	s_lshl_b32 s50, s53, 6
	s_add_i32 s15, s15, s50
	v_lshl_add_u32 v13, v0, 2, s15
	ds_read_b32 v13, v13
	s_and_b32 s15, s52, 16
	s_waitcnt lgkmcnt(0)
	v_lshrrev_b32_e32 v13, s15, v13
	v_and_b32_e32 v13, 0xffff, v13
